# NSA slc/win loops: O accumulators stay in place (copies removed); DA main loop: softmax exp/cvt/sum interleaved into PV MFMA clusters, negm refresh behind a branch
# baseline (speedup 1.0000x reference)
; template <int VSTR, int NDVB> DI void pv64(f32x16 (&O)[NDVB], const lds8* vp, const bf16x8 (&P)[4]) {
;   bf16x8 f[2][NDVB];
; #pragma unroll
;   for (int d = 0; d < NDVB; ++d) { const s16x4 lo = trrd(vp + d * 64), hi = trrd(vp + 8 * VSTR + d * 64); f[0][d] = __builtin_shufflevector(lo, hi, 0, 1, 2, 3, 4, 5, 6, 7); }
; #pragma unroll
;   for (int kk = 0; kk < 4; ++kk) {
;     if (kk < 3) {
; #pragma unroll
;       for (int d = 0; d < NDVB; ++d) { const s16x4 lo = trrd(vp + (16 * (kk + 1)) * VSTR + d * 64), hi = trrd(vp + (16 * (kk + 1) + 8) * VSTR + d * 64);
;         f[(kk + 1) & 1][d] = __builtin_shufflevector(lo, hi, 0, 1, 2, 3, 4, 5, 6, 7); }
;     }
;     SBAR();
;     __builtin_amdgcn_s_setprio(1);
; #pragma unroll
;     for (int d = 0; d < NDVB; ++d) O[d] = MFMA32(f[kk & 1][d], P[kk], O[d]);
;     __builtin_amdgcn_s_setprio(0);
;     SBAR();
;   }
; }
; template <int NDVB, bool HAS_NEXT> DI void softmax_def(f32x16& sa0, f32x16& sa1, f32x16& sb0, f32x16& sb1, f32x16 (&O)[NDVB], float& muse, float& l, bool first, bf16x8 (&P)[4], bool check = true) {
;     ...
;   float sum = 0.f;
; #pragma unroll
;   for (int i = 0; i < 16; ++i) { sa0[i] = __builtin_amdgcn_exp2f(sa0[i]); sum += sa0[i]; }
; #pragma unroll
;   for (int i = 0; i < 16; ++i) { sa1[i] = __builtin_amdgcn_exp2f(sa1[i]); sum += sa1[i]; }
;   l += sum;
;   u32x4 w;
;   w.x = cvtpk(sa0[0], sa0[1]); w.y = cvtpk(sa0[2], sa0[3]); w.z = cvtpk(sa0[4], sa0[5]); w.w = cvtpk(sa0[6], sa0[7]); P[0] = __builtin_bit_cast(bf16x8, w);
;   w.x = cvtpk(sa0[8], sa0[9]); w.y = cvtpk(sa0[10], sa0[11]); w.z = cvtpk(sa0[12], sa0[13]); w.w = cvtpk(sa0[14], sa0[15]); P[1] = __builtin_bit_cast(bf16x8, w);
;   w.x = cvtpk(sa1[0], sa1[1]); w.y = cvtpk(sa1[2], sa1[3]); w.z = cvtpk(sa1[4], sa1[5]); w.w = cvtpk(sa1[6], sa1[7]); P[2] = __builtin_bit_cast(bf16x8, w);
;   w.x = cvtpk(sa1[8], sa1[9]); w.y = cvtpk(sa1[10], sa1[11]); w.z = cvtpk(sa1[12], sa1[13]); w.w = cvtpk(sa1[14], sa1[15]); P[3] = __builtin_bit_cast(bf16x8, w);
; }
; template <bool LOAD2, bool MASK>
; DI void da_step(lds8* lds, const DaCtx& cx, int t, const bf16x8 (&q)[4], f32x16 (&O)[4], float& muse, float& l, f32x16& negm) {
;   u32x4 kr0, kr1, vr0, vr1;
;   if (LOAD2) { const size_t ro = (size_t)(t + 2) * 64;
;     kr0 = *(const u32x4*)(cx.kg + (ro + cx.sr0) * DM + cx.sc0 * 8); kr1 = *(const u32x4*)(cx.kg + (ro + cx.sr1) * DM + cx.sc1 * 8);
.LBB0_851:
	s_nop 3
	v_add_u32_e32 v145, s20, v140
	v_add_u32_e32 v145, 0xffffbcc0, v145
	ds_read_b64_tr_b16 v[232:233], v145 offset:0
	ds_read_b64_tr_b16 v[234:235], v145 offset:2432
	ds_read_b64_tr_b16 v[236:237], v145 offset:64
	ds_read_b64_tr_b16 v[238:239], v145 offset:2496
	ds_read_b64_tr_b16 v[240:241], v145 offset:128
	ds_read_b64_tr_b16 v[242:243], v145 offset:2560
	ds_read_b64_tr_b16 v[244:245], v145 offset:192
	ds_read_b64_tr_b16 v[246:247], v145 offset:2624
	ds_read_b64_tr_b16 v[146:147], v145 offset:4864
	ds_read_b64_tr_b16 v[148:149], v145 offset:7296
	ds_read_b64_tr_b16 v[150:151], v145 offset:4928
	ds_read_b64_tr_b16 v[152:153], v145 offset:7360
	ds_read_b64_tr_b16 v[154:155], v145 offset:4992
	ds_read_b64_tr_b16 v[156:157], v145 offset:7424
	ds_read_b64_tr_b16 v[192:193], v145 offset:5056
	ds_read_b64_tr_b16 v[194:195], v145 offset:7488
	s_mul_i32 s21, s21, 3
	s_add_i32 s21, s21, -1
	v_exp_f32_e32 v96, v96
	v_exp_f32_e32 v97, v97
	v_exp_f32_e32 v98, v98
	v_exp_f32_e32 v99, v99
	v_exp_f32_e32 v100, v100
	v_exp_f32_e32 v101, v101
	v_exp_f32_e32 v102, v102
	v_exp_f32_e32 v103, v103
	v_cvt_pk_bf16_f32 v216, v96, v97
	v_cvt_pk_bf16_f32 v217, v98, v99
	v_cvt_pk_bf16_f32 v218, v100, v101
	v_cvt_pk_bf16_f32 v219, v102, v103
	v_readfirstlane_b32 s22, v200
	s_nop 1
	s_bitcmp1_b32 s22, 8
	s_cbranch_scc0 .Lda_nobar_b
	s_barrier
.Lda_nobar_b:
	s_setprio 1
	s_waitcnt lgkmcnt(14)
	v_mfma_f32_32x32x16_bf16 v[0:15], v[232:235], v[216:219], v[0:15]
	v_exp_f32_e32 v104, v104
	v_exp_f32_e32 v105, v105
	v_exp_f32_e32 v106, v106
	s_waitcnt lgkmcnt(12)
	v_mfma_f32_32x32x16_bf16 v[16:31], v[236:239], v[216:219], v[16:31]
	v_exp_f32_e32 v107, v107
	v_exp_f32_e32 v108, v108
	v_exp_f32_e32 v109, v109
	s_waitcnt lgkmcnt(10)
	v_mfma_f32_32x32x16_bf16 v[32:47], v[240:243], v[216:219], v[32:47]
	v_exp_f32_e32 v110, v110
	v_exp_f32_e32 v111, v111
	v_add_f32_e32 v142, 0, v96
	v_add_f32_e32 v142, v97, v142
	s_waitcnt lgkmcnt(8)
	v_mfma_f32_32x32x16_bf16 v[48:63], v[244:247], v[216:219], v[48:63]
	v_cvt_pk_bf16_f32 v220, v104, v105
	v_cvt_pk_bf16_f32 v221, v106, v107
	v_cvt_pk_bf16_f32 v222, v108, v109
	v_cvt_pk_bf16_f32 v223, v110, v111
	v_add_f32_e32 v142, v98, v142
	v_add_f32_e32 v142, v99, v142
	s_setprio 0
	ds_read_b64_tr_b16 v[232:233], v145 offset:9728
	ds_read_b64_tr_b16 v[234:235], v145 offset:12160
	ds_read_b64_tr_b16 v[236:237], v145 offset:9792
	ds_read_b64_tr_b16 v[238:239], v145 offset:12224
	ds_read_b64_tr_b16 v[240:241], v145 offset:9856
	ds_read_b64_tr_b16 v[242:243], v145 offset:12288
	ds_read_b64_tr_b16 v[244:245], v145 offset:9920
	ds_read_b64_tr_b16 v[246:247], v145 offset:12352
	s_setprio 1
	s_waitcnt lgkmcnt(14)
	v_mfma_f32_32x32x16_bf16 v[0:15], v[146:149], v[220:223], v[0:15]
	v_exp_f32_e32 v80, v80
	v_exp_f32_e32 v81, v81
	v_add_f32_e32 v142, v100, v142
	v_add_f32_e32 v142, v101, v142
	s_waitcnt lgkmcnt(12)
	v_mfma_f32_32x32x16_bf16 v[16:31], v[150:153], v[220:223], v[16:31]
	v_exp_f32_e32 v82, v82
	v_exp_f32_e32 v83, v83
	v_add_f32_e32 v142, v102, v142
	v_add_f32_e32 v142, v103, v142
	s_waitcnt lgkmcnt(10)
	v_mfma_f32_32x32x16_bf16 v[32:47], v[154:157], v[220:223], v[32:47]
	v_exp_f32_e32 v84, v84
	v_exp_f32_e32 v85, v85
	v_add_f32_e32 v142, v104, v142
	v_add_f32_e32 v142, v105, v142
	s_waitcnt lgkmcnt(8)
	v_mfma_f32_32x32x16_bf16 v[48:63], v[192:195], v[220:223], v[48:63]
	v_exp_f32_e32 v86, v86
	v_exp_f32_e32 v87, v87
	v_add_f32_e32 v142, v106, v142
	v_add_f32_e32 v142, v107, v142
	v_add_f32_e32 v142, v108, v142
	v_add_f32_e32 v142, v109, v142
	v_add_f32_e32 v142, v110, v142
	v_add_f32_e32 v142, v111, v142
	v_cvt_pk_bf16_f32 v224, v80, v81
	v_cvt_pk_bf16_f32 v225, v82, v83
	v_cvt_pk_bf16_f32 v226, v84, v85
	v_cvt_pk_bf16_f32 v227, v86, v87
	s_setprio 0
	ds_read_b64_tr_b16 v[250:251], v145 offset:17088
	ds_read_b64_tr_b16 v[108:109], v145 offset:14720
	ds_read_b64_tr_b16 v[110:111], v145 offset:17152
	ds_read_b64_tr_b16 v[146:147], v145 offset:14784
	ds_read_b64_tr_b16 v[150:151], v145 offset:14592
	ds_read_b64_tr_b16 v[152:153], v145 offset:17024
	ds_read_b64_tr_b16 v[248:249], v145 offset:14656
	ds_read_b64_tr_b16 v[148:149], v145 offset:17216
	s_setprio 1
	s_waitcnt lgkmcnt(14)
	v_mfma_f32_32x32x16_bf16 v[0:15], v[232:235], v[224:227], v[0:15]
	v_exp_f32_e32 v88, v88
	v_exp_f32_e32 v89, v89
	v_add_f32_e32 v142, v80, v142
	v_add_f32_e32 v142, v81, v142
	s_waitcnt lgkmcnt(12)
	v_mfma_f32_32x32x16_bf16 v[16:31], v[236:239], v[224:227], v[16:31]
	v_exp_f32_e32 v90, v90
	v_exp_f32_e32 v91, v91
	v_add_f32_e32 v142, v82, v142
	v_add_f32_e32 v142, v83, v142
	s_waitcnt lgkmcnt(10)
	v_mfma_f32_32x32x16_bf16 v[32:47], v[240:243], v[224:227], v[32:47]
	v_exp_f32_e32 v92, v92
	v_exp_f32_e32 v93, v93
	v_add_f32_e32 v142, v84, v142
	v_add_f32_e32 v142, v85, v142
	s_waitcnt lgkmcnt(8)
	v_mfma_f32_32x32x16_bf16 v[48:63], v[244:247], v[224:227], v[48:63]
	v_exp_f32_e32 v94, v94
	v_exp_f32_e32 v95, v95
	v_add_f32_e32 v142, v86, v142
	v_add_f32_e32 v142, v87, v142
	v_cvt_pk_bf16_f32 v228, v88, v89
	v_cvt_pk_bf16_f32 v229, v90, v91
	v_cvt_pk_bf16_f32 v230, v92, v93
	v_cvt_pk_bf16_f32 v231, v94, v95
	s_setprio 0
	s_setprio 1
	s_waitcnt lgkmcnt(2)
	v_mfma_f32_32x32x16_bf16 v[0:15], v[150:153], v[228:231], v[0:15]
	v_add_f32_e32 v142, v88, v142
	v_add_f32_e32 v142, v89, v142
	v_add_f32_e32 v142, v90, v142
	v_add_f32_e32 v142, v91, v142
	s_waitcnt lgkmcnt(1)
	v_mfma_f32_32x32x16_bf16 v[16:31], v[248:251], v[228:231], v[16:31]
	v_add_f32_e32 v142, v92, v142
	v_add_f32_e32 v142, v93, v142
	v_add_f32_e32 v142, v94, v142
	v_add_f32_e32 v142, v95, v142
	v_mfma_f32_32x32x16_bf16 v[32:47], v[108:111], v[228:231], v[32:47]
	v_add_f32_e32 v176, v128, v142
	v_cmp_neq_f32_e32 vcc, v129, v177
	v_add_u32_e32 v140, 0x9800, v140
	v_add_u32_e32 v141, 0x9800, v141
	v_lshl_add_u64 v[130:131], v[130:131], 0, s[90:91]
	v_lshl_add_u64 v[132:133], v[132:133], 0, s[90:91]
	s_waitcnt lgkmcnt(0)
	v_mfma_f32_32x32x16_bf16 v[48:63], v[146:149], v[228:231], v[48:63]
	s_mov_b32 s22, 0x80000000
	s_cmp_eq_u64 vcc, 0
	s_cbranch_scc1 .Lda_negm_same
	v_xor_b32_e32 v79, s22, v129
	v_xor_b32_e32 v78, s22, v129
	v_xor_b32_e32 v77, s22, v129
	v_xor_b32_e32 v76, s22, v129
	v_xor_b32_e32 v75, s22, v129
	v_xor_b32_e32 v74, s22, v129
	v_xor_b32_e32 v73, s22, v129
	v_xor_b32_e32 v72, s22, v129
	v_xor_b32_e32 v71, s22, v129
	v_xor_b32_e32 v70, s22, v129
	v_xor_b32_e32 v69, s22, v129
	v_xor_b32_e32 v68, s22, v129
	v_xor_b32_e32 v67, s22, v129
	v_xor_b32_e32 v66, s22, v129
	v_xor_b32_e32 v65, s22, v129
	v_xor_b32_e32 v64, s22, v129
.Lda_negm_same:
	s_setprio 0
	s_add_i32 s20, s10, s20
	s_cmp_lg_u32 s21, s12
	s_cselect_b32 s12, s20, 0x13000
	s_add_i32 s12, s12, 0
	s_add_i32 s11, s11, 1
	s_add_i32 s10, s10, 0x9800
	v_add3_u32 v80, s12, v137, v186
	v_add3_u32 v81, s12, v138, v186
	v_readfirstlane_b32 s20, v200
	s_nop 1
	s_bitcmp1_b32 s20, 8
	s_cbranch_scc1 .Lda_nobar_a
	s_barrier

; DI unsigned cvtpk(float lo, float hi) { f32x2_t v = {lo, hi}; bf16x2_t b = __builtin_convertvector(v, bf16x2_t); return __builtin_bit_cast(unsigned, b); }
; #define NS_GLOAD(k_, KR, VR) do { const int jj = __builtin_amdgcn_readfirstlane(jl[(k_)]); KR = *(const u32x4*)(kg + (size_t)(64 * jj + sr) * pitch + sc * 8); VR = *(const u32x4*)(vg + (size_t)(64 * jj + sr) * pitch + sc * 8); } while (0)
; #define NS_LSTORE(st_, KR, VR) do { lds8* b = lds + (st_) * NS_STAGE; *(LAS u32x4*)(b + sr * NS_STR + sc * 16) = KR; *(LAS u32x4*)(b + 64 * NS_STR + sr * NS_STR + sc * 16) = VR; } while (0)
; template <int NDVB, bool HAS_NEXT> DI void softmax_def(f32x16& sa0, f32x16& sa1, f32x16& sb0, f32x16& sb1, f32x16 (&O)[NDVB], float& muse, float& l, bool first, bf16x8 (&P)[4], bool check = true) {
;     ...
;   float sum = 0.f;
; #pragma unroll
;   for (int i = 0; i < 16; ++i) { sa0[i] = __builtin_amdgcn_exp2f(sa0[i]); sum += sa0[i]; }
; #pragma unroll
;   for (int i = 0; i < 16; ++i) { sa1[i] = __builtin_amdgcn_exp2f(sa1[i]); sum += sa1[i]; }
;   l += sum;
;   u32x4 w;
;   w.x = cvtpk(sa0[0], sa0[1]); w.y = cvtpk(sa0[2], sa0[3]); w.z = cvtpk(sa0[4], sa0[5]); w.w = cvtpk(sa0[6], sa0[7]); P[0] = __builtin_bit_cast(bf16x8, w);
;   w.x = cvtpk(sa0[8], sa0[9]); w.y = cvtpk(sa0[10], sa0[11]); w.z = cvtpk(sa0[12], sa0[13]); w.w = cvtpk(sa0[14], sa0[15]); P[1] = __builtin_bit_cast(bf16x8, w);
;   w.x = cvtpk(sa1[0], sa1[1]); w.y = cvtpk(sa1[2], sa1[3]); w.z = cvtpk(sa1[4], sa1[5]); w.w = cvtpk(sa1[6], sa1[7]); P[2] = __builtin_bit_cast(bf16x8, w);
;   w.x = cvtpk(sa1[8], sa1[9]); w.y = cvtpk(sa1[10], sa1[11]); w.z = cvtpk(sa1[12], sa1[13]); w.w = cvtpk(sa1[14], sa1[15]); P[3] = __builtin_bit_cast(bf16x8, w);
; template <int MODE>
; DI void nsa_branch(lds8* lds, const bf16_t* kg, const bf16_t* vg, int pitch, unsigned tiles, const bf16x8 (&q)[4], int qpos, unsigned mybits, int blk,
;                    f32x16 (&O)[2], float& muse, float& l, int tid, int lane, int grp, CmpCap& cap) {
;     ...
;   NS_GLOAD(0, kra, vra); NS_LSTORE(0, kra, vra);
;   if (ntl > 1) { NS_GLOAD(1, kra, vra); NS_LSTORE(1, kra, vra); }
;   __syncthreads();
;   f32x16 s0, s1, du0, du1; bf16x8 P[4];
;   int st_cur = 0;
;     ...
;   for (int t = 0; t < ntl; ++t) {
;     NS_STEP(kra, vra, 0);
;     ++t; if (t >= ntl) break;
;     NS_STEP(kra, vra, 1);
;   }
.LBB0_951:
	v_exp_f32_e32 v108, v60
	v_add_u32_e32 v60, s95, v216
	v_exp_f32_e32 v96, v48
	v_exp_f32_e32 v97, v49
	v_exp_f32_e32 v98, v50
	v_exp_f32_e32 v99, v51
	v_exp_f32_e32 v100, v52
	v_exp_f32_e32 v101, v53
	v_exp_f32_e32 v102, v54
	v_exp_f32_e32 v103, v55
	v_exp_f32_e32 v104, v56
	v_exp_f32_e32 v105, v57
	v_exp_f32_e32 v106, v58
	v_exp_f32_e32 v107, v59
	v_exp_f32_e32 v124, v44
	v_exp_f32_e32 v125, v45
	v_exp_f32_e32 v126, v46
	v_exp_f32_e32 v127, v47
	ds_read_b64_tr_b16 v[44:45], v60 offset:9216
	ds_read_b64_tr_b16 v[46:47], v60 offset:10368
	ds_read_b64_tr_b16 v[50:51], v60 offset:10432
	ds_read_b64_tr_b16 v[48:49], v60 offset:9280
	ds_read_b64_tr_b16 v[52:53], v60 offset:11520
	ds_read_b64_tr_b16 v[54:55], v60 offset:12672
	ds_read_b64_tr_b16 v[58:59], v60 offset:12736
	ds_read_b64_tr_b16 v[56:57], v60 offset:11584
	v_exp_f32_e32 v109, v61
	v_exp_f32_e32 v110, v62
	v_exp_f32_e32 v111, v63
	v_exp_f32_e32 v112, v32
	v_exp_f32_e32 v113, v33
	v_exp_f32_e32 v114, v34
	v_exp_f32_e32 v115, v35
	v_exp_f32_e32 v116, v36
	v_exp_f32_e32 v117, v37
	v_exp_f32_e32 v118, v38
	v_exp_f32_e32 v119, v39
	v_exp_f32_e32 v120, v40
	v_exp_f32_e32 v121, v41
	v_exp_f32_e32 v122, v42
	v_exp_f32_e32 v123, v43
	v_cvt_pk_bf16_f32 v32, v96, v97
	v_cvt_pk_bf16_f32 v33, v98, v99
	v_cvt_pk_bf16_f32 v34, v100, v101
	v_cvt_pk_bf16_f32 v35, v102, v103
	v_cvt_pk_bf16_f32 v36, v104, v105
	v_cvt_pk_bf16_f32 v37, v106, v107
	v_cvt_pk_bf16_f32 v38, v108, v109
	v_cvt_pk_bf16_f32 v39, v110, v111
	v_cvt_pk_bf16_f32 v40, v112, v113
	v_cvt_pk_bf16_f32 v41, v114, v115
	v_cvt_pk_bf16_f32 v42, v116, v117
	v_cvt_pk_bf16_f32 v43, v118, v119
	v_cvt_pk_bf16_f32 v140, v120, v121
	v_cvt_pk_bf16_f32 v141, v122, v123
	v_cvt_pk_bf16_f32 v142, v124, v125
	v_cvt_pk_bf16_f32 v143, v126, v127
	s_setprio 1
	s_waitcnt lgkmcnt(6)
	v_mfma_f32_32x32x16_bf16 v[0:15], v[44:47], v[32:35], v[0:15]
	s_waitcnt lgkmcnt(4)
	v_mfma_f32_32x32x16_bf16 v[16:31], v[48:51], v[32:35], v[16:31]
	s_setprio 0
	ds_read_b64_tr_b16 v[32:33], v60 offset:13824
	ds_read_b64_tr_b16 v[34:35], v60 offset:14976
	ds_read_b64_tr_b16 v[46:47], v60 offset:15040
	ds_read_b64_tr_b16 v[44:45], v60 offset:13888
	s_setprio 1
	s_waitcnt lgkmcnt(6)
	v_mfma_f32_32x32x16_bf16 v[0:15], v[52:55], v[36:39], v[0:15]
	s_waitcnt lgkmcnt(4)
	v_mfma_f32_32x32x16_bf16 v[16:31], v[56:59], v[36:39], v[16:31]
	s_setprio 0
	ds_read_b64_tr_b16 v[48:49], v60 offset:16128
	ds_read_b64_tr_b16 v[50:51], v60 offset:17280
	ds_read_b64_tr_b16 v[146:147], v60 offset:17344
	ds_read_b64_tr_b16 v[144:145], v60 offset:16192
	s_setprio 1
	s_waitcnt lgkmcnt(6)
	v_mfma_f32_32x32x16_bf16 v[0:15], v[32:35], v[40:43], v[0:15]
	s_waitcnt lgkmcnt(4)
	v_mfma_f32_32x32x16_bf16 v[16:31], v[44:47], v[40:43], v[16:31]
	s_setprio 0
	s_setprio 1
	s_waitcnt lgkmcnt(2)
	v_mfma_f32_32x32x16_bf16 v[0:15], v[48:51], v[140:143], v[0:15]
	s_waitcnt lgkmcnt(0)
	v_mfma_f32_32x32x16_bf16 v[16:31], v[144:147], v[140:143], v[16:31]
	s_setprio 0
	s_andn2_b64 vcc, exec, s[82:83]
	s_cbranch_vccnz .LBB0_953
	s_addk_i32 s94, 0xb800
	s_cmp_lg_u32 s6, 0
	s_cselect_b32 s82, s94, 0x9000
	v_add_u32_e32 v32, s82, v215
	s_waitcnt vmcnt(1)
	ds_write_b128 v32, v[128:131]
	s_waitcnt vmcnt(0)
	ds_write_b128 v32, v[132:135] offset:9216
.LBB0_953:
	v_add_f32_e32 v32, 0, v96
	v_add_f32_e32 v32, v97, v32
	v_add_f32_e32 v32, v98, v32
	v_add_f32_e32 v32, v99, v32
	v_add_f32_e32 v32, v100, v32
	v_add_f32_e32 v32, v101, v32
	v_add_f32_e32 v32, v102, v32
	v_add_f32_e32 v32, v103, v32
	v_add_f32_e32 v32, v104, v32
	v_add_f32_e32 v32, v105, v32
	v_add_f32_e32 v32, v106, v32
	v_add_f32_e32 v32, v107, v32
	v_add_f32_e32 v32, v108, v32
	v_add_f32_e32 v32, v109, v32
	v_add_f32_e32 v32, v110, v32
	v_add_f32_e32 v32, v111, v32
	v_add_f32_e32 v32, v112, v32
	v_add_f32_e32 v32, v113, v32
	v_add_f32_e32 v32, v114, v32
	v_add_f32_e32 v32, v115, v32
	v_add_f32_e32 v32, v116, v32
	v_add_f32_e32 v32, v117, v32
	v_add_f32_e32 v32, v118, v32
	v_add_f32_e32 v32, v119, v32
	v_add_f32_e32 v32, v120, v32
	v_add_f32_e32 v32, v121, v32
	v_add_f32_e32 v32, v122, v32
	v_add_f32_e32 v32, v123, v32
	v_add_f32_e32 v32, v124, v32
	v_add_f32_e32 v32, v125, v32
	v_add_f32_e32 v32, v126, v32
	v_add_f32_e32 v32, v127, v32
	s_add_i32 s84, s89, -2
	v_add_f32_e32 v139, v219, v32
	s_mov_b64 s[82:83], -1
	s_cmp_ge_u32 s84, s88
	s_mov_b64 s[84:85], -1
	s_movk_i32 s95, 0x1ff
	s_waitcnt lgkmcnt(0)
	s_barrier
	s_cbranch_scc1 .LBB0_937
	s_cmp_lt_u32 s89, s88
	s_cselect_b64 s[82:83], -1, 0
	s_cmp_ge_u32 s89, s88
	s_cbranch_scc1 .LBB0_956
	v_mov_b32_e32 v32, s90
	ds_read_b32 v32, v32 offset:12
	s_waitcnt lgkmcnt(0)
	v_readfirstlane_b32 s84, v32
	s_nop 1
	v_lshl_add_u32 v32, s84, 6, v212
	v_ashrrev_i32_e32 v33, 31, v32
	v_lshlrev_b64 v[32:33], 9, v[32:33]
	v_lshl_add_u64 v[34:35], v[194:195], 0, v[32:33]
	v_lshl_add_u64 v[32:33], v[196:197], 0, v[32:33]
	global_load_dwordx4 v[128:131], v[34:35], off
	global_load_dwordx4 v[132:135], v[32:33], off
; #define LAS __attribute__((address_space(3)))
; #define MFMA32(a, b, c) __builtin_amdgcn_mfma_f32_32x32x16_bf16((a), (b), (c), 0, 0, 0)
; #define SBAR() __builtin_amdgcn_sched_barrier(0)
; template <int KSTR> DI void qk64b(f32x16& s0, f32x16& s1, const lds8* kp, const bf16x8 (&q)[4], float bias) {
;   bf16x8 a[8];
; #pragma unroll
;   for (int ks = 0; ks < 4; ++ks) { a[2 * ks] = *(const LAS bf16x8*)(kp + ks * 32); a[2 * ks + 1] = *(const LAS bf16x8*)(kp + 32 * KSTR + ks * 32); }
; #pragma unroll
;   for (int i = 0; i < 16; ++i) { s0[i] = bias; s1[i] = bias; }
;   SBAR();
;   __builtin_amdgcn_s_setprio(1);
; #pragma unroll
;   for (int ks = 0; ks < 4; ++ks) { s0 = MFMA32(a[2 * ks], q[ks], s0); s1 = MFMA32(a[2 * ks + 1], q[ks], s1); }
;   __builtin_amdgcn_s_setprio(0);
;   SBAR();
; }
; template <int MODE, int SLOT> DI void ns_valu(volatile LAS int* jl, int t, int ntl, int qpos, int h, int blk, f32x16& s0, f32x16& s1, f32x16& du0, f32x16& du1, f32x16 (&O)[2], float& muse, float& l, bf16x8 (&P)[4], CmpCap& cap) {
;     if (t < ntl) {
;       const int j = __builtin_amdgcn_readfirstlane(jl[t]);
;       if (MODE == 0) {
;         const int lim = ((qpos - 31) >> 4) - 64 * j - 4 * h;
; #pragma unroll
;         for (int i = 0; i < 16; ++i) { const int ci = (i & 3) + 8 * (i >> 2); if (ci > lim) s0[i] = NEG; if (ci + 32 > lim) s1[i] = NEG; }
;       } else if (MODE == 1) {
;         if (j == blk) {
;           const int lim = qpos - 64 * j - 4 * h;
; #pragma unroll
;           for (int i = 0; i < 16; ++i) { const int ci = (i & 3) + 8 * (i >> 2); if (ci > lim) s0[i] = NEG; if (ci + 32 > lim) s1[i] = NEG; }
;         }
.LBB0_956:
	s_add_i32 s84, s6, 1
	s_cmp_lg_u32 s6, 2
	s_cselect_b32 s6, s84, 0
	v_mov_b32_e32 v140, s90
	ds_read_b32 v32, v140 offset:4
	s_mul_i32 s86, s6, 0x4800
	s_add_i32 s87, s86, 0
	v_add_u32_e32 v60, s87, v213
	s_waitcnt lgkmcnt(0)
	v_readfirstlane_b32 s84, v32
	s_nop 1
	v_lshrrev_b32_e32 v32, s84, v137
	v_and_b32_e32 v32, 1, v32
	v_cmp_eq_u32_e32 vcc, 1, v32
	ds_read_b128 v[32:35], v60 offset:4608
	ds_read_b128 v[36:39], v60
	ds_read_b128 v[40:43], v60 offset:32
	ds_read_b128 v[44:47], v60 offset:4640
	ds_read_b128 v[48:51], v60 offset:64
	ds_read_b128 v[52:55], v60 offset:4672
	ds_read_b128 v[56:59], v60 offset:96
	ds_read_b128 v[60:63], v60 offset:4704
	v_cndmask_b32_e64 v96, v207, -v138, vcc
	v_mov_b32_e32 v97, v96
	v_mov_b32_e32 v98, v96
	v_mov_b32_e32 v99, v96
	v_mov_b32_e32 v100, v96
	v_mov_b32_e32 v101, v96
	v_mov_b32_e32 v102, v96
	v_mov_b32_e32 v103, v96
	v_mov_b32_e32 v104, v96
	v_mov_b32_e32 v105, v96
	v_mov_b32_e32 v106, v96
	v_mov_b32_e32 v107, v96
	v_mov_b32_e32 v108, v96
	v_mov_b32_e32 v109, v96
	v_mov_b32_e32 v110, v96
	v_mov_b32_e32 v111, v96
	s_setprio 1
	s_waitcnt lgkmcnt(6)
	v_mfma_f32_32x32x16_bf16 v[112:127], v[36:39], v[160:163], v[96:111]
	v_mfma_f32_32x32x16_bf16 v[96:111], v[32:35], v[160:163], v[96:111]
	s_waitcnt lgkmcnt(5)
	v_mfma_f32_32x32x16_bf16 v[112:127], v[40:43], v[168:171], v[112:127]
	s_waitcnt lgkmcnt(4)
	v_mfma_f32_32x32x16_bf16 v[96:111], v[44:47], v[168:171], v[96:111]
	s_waitcnt lgkmcnt(3)
	v_mfma_f32_32x32x16_bf16 v[112:127], v[48:51], v[164:167], v[112:127]
	s_waitcnt lgkmcnt(2)
	v_mfma_f32_32x32x16_bf16 v[96:111], v[52:55], v[164:167], v[96:111]
	s_waitcnt lgkmcnt(1)
	v_mfma_f32_32x32x16_bf16 v[112:127], v[56:59], v[172:175], v[112:127]
	s_waitcnt lgkmcnt(0)
	v_mfma_f32_32x32x16_bf16 v[96:111], v[60:63], v[172:175], v[96:111]
	s_setprio 0
	ds_read_b32 v32, v140 offset:4
	s_waitcnt lgkmcnt(0)
	v_readfirstlane_b32 s84, v32
	s_cmp_lg_u32 s84, s77
	s_cbranch_scc1 .LBB0_960
	s_and_b64 vcc, s[70:71], s[66:67]
	s_nop 4
	v_cndmask_b32_e32 v109, v109, v207, vcc
	s_and_b64 vcc, vcc, s[62:63]
	v_cndmask_b32_e32 v108, v108, v207, vcc
	s_and_b64 vcc, vcc, s[58:59]
	v_cndmask_b32_e32 v107, v107, v207, vcc
	s_and_b64 vcc, vcc, s[54:55]
	v_cndmask_b32_e32 v106, v106, v207, vcc
	s_and_b64 vcc, vcc, s[50:51]
	v_cndmask_b32_e32 v105, v105, v207, vcc
	s_and_b64 vcc, vcc, s[46:47]
	v_cndmask_b32_e32 v104, v104, v207, vcc
	s_and_b64 vcc, vcc, s[42:43]
	v_cndmask_b32_e32 v103, v103, v207, vcc
	s_and_b64 vcc, vcc, s[38:39]
	v_cndmask_b32_e32 v102, v102, v207, vcc
	s_and_b64 vcc, vcc, s[34:35]
	v_cndmask_b32_e32 v101, v101, v207, vcc
	s_and_b64 vcc, vcc, s[28:29]
	v_cndmask_b32_e32 v100, v100, v207, vcc
	s_and_b64 vcc, vcc, s[24:25]
	v_cndmask_b32_e32 v99, v99, v207, vcc
	s_and_b64 vcc, vcc, s[20:21]
	v_cndmask_b32_e32 v98, v98, v207, vcc
	s_and_b64 vcc, vcc, s[16:17]
	v_cndmask_b32_e32 v97, v97, v207, vcc
	s_and_b64 vcc, vcc, s[12:13]
	v_cndmask_b32_e64 v110, v110, v207, s[70:71]
	v_cndmask_b32_e32 v96, v96, v207, vcc
	s_and_saveexec_b64 s[84:85], s[74:75]
	s_mov_b32 s94, 0xf149f2ca
	v_mov_b32_e32 v111, s94
	s_or_b64 exec, exec, s[84:85]
	s_and_b64 vcc, s[72:73], s[68:69]
	v_cndmask_b32_e32 v126, v126, v207, vcc
	s_and_b64 vcc, vcc, s[64:65]
	v_cndmask_b32_e32 v125, v125, v207, vcc
	s_and_b64 vcc, vcc, s[60:61]
	v_cndmask_b32_e32 v124, v124, v207, vcc
	s_and_b64 vcc, vcc, s[56:57]
	v_cndmask_b32_e32 v123, v123, v207, vcc
	s_and_b64 vcc, vcc, s[52:53]
	v_cndmask_b32_e32 v122, v122, v207, vcc
	s_and_b64 vcc, vcc, s[48:49]
	v_cndmask_b32_e32 v121, v121, v207, vcc
	s_and_b64 vcc, vcc, s[44:45]
	v_cndmask_b32_e32 v120, v120, v207, vcc
	s_and_b64 vcc, vcc, s[40:41]
	v_cndmask_b32_e32 v119, v119, v207, vcc
	s_and_b64 vcc, vcc, s[36:37]
	v_cndmask_b32_e32 v118, v118, v207, vcc
	s_and_b64 vcc, vcc, s[30:31]
	v_cndmask_b32_e32 v117, v117, v207, vcc
	s_and_b64 vcc, vcc, s[26:27]
	v_cndmask_b32_e32 v116, v116, v207, vcc
	s_and_b64 vcc, vcc, s[22:23]
	v_cndmask_b32_e32 v115, v115, v207, vcc
	s_and_b64 vcc, vcc, s[18:19]
	v_cndmask_b32_e32 v114, v114, v207, vcc
	s_and_b64 vcc, vcc, s[14:15]
	v_cndmask_b32_e32 v113, v113, v207, vcc
	s_and_b64 vcc, vcc, s[10:11]
	v_cndmask_b32_e64 v127, v127, v207, s[72:73]
	v_cndmask_b32_e32 v112, v112, v207, vcc
; DI float rowmax32(const f32x16& s0, const f32x16& s1) {
;   float a = fmaxf(fmaxf(s0[0], s0[1]), s1[0]), b = fmaxf(fmaxf(s0[2], s0[3]), s1[1]); a = fmaxf(fmaxf(a, s1[2]), s1[3]);
; #pragma unroll
;   for (int r = 4; r < 16; r += 4) { a = fmaxf(fmaxf(a, s0[r]), s0[r + 1]); b = fmaxf(fmaxf(b, s0[r + 2]), s0[r + 3]); a = fmaxf(fmaxf(a, s1[r]), s1[r + 1]); b = fmaxf(fmaxf(b, s1[r + 2]), s1[r + 3]); }
;   const float m = fmaxf(a, b);
;   return fmaxf(m, __shfl_xor(m, 32));
; }
; template <int NDVB, bool HAS_NEXT> DI void softmax_def(f32x16& sa0, f32x16& sa1, f32x16& sb0, f32x16& sb1, f32x16 (&O)[NDVB], float& muse, float& l, bool first, bf16x8 (&P)[4], bool check = true) {
;   float mx = 0.f;
;   if (check) mx = rowmax32(sa0, sa1);
;   if (check && (first || __any(mx > 8.f))) {
;     float dl = first ? mx : fmaxf(mx, 0.f);
;     if (mx < -1e29f) dl = 0.f;
;     const float alpha = __builtin_amdgcn_exp2f(-dl);
;     muse += dl; l *= alpha;
; #pragma unroll
;     for (int i = 0; i < 16; ++i) { sa0[i] -= dl; sa1[i] -= dl; }
;     if (HAS_NEXT) {
; #pragma unroll
;       for (int i = 0; i < 16; ++i) { sb0[i] -= dl; sb1[i] -= dl; }
;     }
; #pragma unroll
;     for (int d = 0; d < NDVB; ++d)
; #pragma unroll
;       for (int i = 0; i < 16; ++i) O[d][i] *= alpha;
;   }
.LBB0_960:
	s_nop 3
	v_max_f32_e32 v32, v113, v113
	v_max_f32_e32 v33, v112, v112
	v_max_f32_e32 v32, v33, v32
	v_max3_f32 v33, v114, v115, v97
	v_max3_f32 v32, v32, v96, v98
	v_max3_f32 v32, v32, v99, v116
	v_max3_f32 v33, v33, v118, v119
	v_max3_f32 v32, v32, v117, v100
	v_max3_f32 v33, v33, v102, v103
	v_max3_f32 v32, v32, v101, v120
	v_max3_f32 v33, v33, v122, v123
	v_max3_f32 v32, v32, v121, v104
	v_max3_f32 v33, v33, v106, v107
	v_max3_f32 v32, v32, v105, v124
	v_max3_f32 v33, v33, v126, v127
	v_max3_f32 v32, v32, v125, v108
	v_max3_f32 v33, v33, v110, v111
	v_max3_f32 v32, v32, v109, v33
	ds_bpermute_b32 v33, v193, v32
	s_waitcnt lgkmcnt(0)
	v_max_f32_e32 v33, v33, v33
	v_max_f32_e32 v32, v32, v33
	v_cmp_lt_f32_e32 vcc, s7, v32
	s_cbranch_vccz .LBB0_963
	v_max_f32_e32 v33, v32, v32
	v_max_f32_e32 v33, 0, v33
	v_cmp_ngt_f32_e32 vcc, s1, v32
	s_nop 1
	v_cndmask_b32_e32 v32, 0, v33, vcc
	v_exp_f32_e64 v142, -v32
	v_add_f32_e32 v138, v138, v32
	v_pk_add_f32 v[112:113], v[112:113], v[32:33] op_sel_hi:[1,0] neg_lo:[0,1] neg_hi:[0,1]
	v_pk_add_f32 v[96:97], v[96:97], v[32:33] op_sel_hi:[1,0] neg_lo:[0,1] neg_hi:[0,1]
	v_mul_f32_e32 v140, v139, v142
	v_pk_add_f32 v[114:115], v[114:115], v[32:33] op_sel_hi:[1,0] neg_lo:[0,1] neg_hi:[0,1]
	v_pk_add_f32 v[98:99], v[98:99], v[32:33] op_sel_hi:[1,0] neg_lo:[0,1] neg_hi:[0,1]
	v_pk_add_f32 v[116:117], v[116:117], v[32:33] op_sel_hi:[1,0] neg_lo:[0,1] neg_hi:[0,1]
	v_pk_add_f32 v[100:101], v[100:101], v[32:33] op_sel_hi:[1,0] neg_lo:[0,1] neg_hi:[0,1]
	v_pk_add_f32 v[118:119], v[118:119], v[32:33] op_sel_hi:[1,0] neg_lo:[0,1] neg_hi:[0,1]
	v_pk_add_f32 v[102:103], v[102:103], v[32:33] op_sel_hi:[1,0] neg_lo:[0,1] neg_hi:[0,1]
	v_pk_add_f32 v[120:121], v[120:121], v[32:33] op_sel_hi:[1,0] neg_lo:[0,1] neg_hi:[0,1]
	v_pk_add_f32 v[104:105], v[104:105], v[32:33] op_sel_hi:[1,0] neg_lo:[0,1] neg_hi:[0,1]
	v_pk_add_f32 v[122:123], v[122:123], v[32:33] op_sel_hi:[1,0] neg_lo:[0,1] neg_hi:[0,1]
	v_pk_add_f32 v[106:107], v[106:107], v[32:33] op_sel_hi:[1,0] neg_lo:[0,1] neg_hi:[0,1]
	v_pk_add_f32 v[124:125], v[124:125], v[32:33] op_sel_hi:[1,0] neg_lo:[0,1] neg_hi:[0,1]
	v_pk_add_f32 v[108:109], v[108:109], v[32:33] op_sel_hi:[1,0] neg_lo:[0,1] neg_hi:[0,1]
	v_pk_add_f32 v[126:127], v[126:127], v[32:33] op_sel_hi:[1,0] neg_lo:[0,1] neg_hi:[0,1]
	v_pk_add_f32 v[110:111], v[110:111], v[32:33] op_sel_hi:[1,0] neg_lo:[0,1] neg_hi:[0,1]
	v_pk_mul_f32 v[30:31], v[30:31], v[142:143] op_sel_hi:[1,0]
	v_pk_mul_f32 v[28:29], v[28:29], v[142:143] op_sel_hi:[1,0]
	v_pk_mul_f32 v[26:27], v[26:27], v[142:143] op_sel_hi:[1,0]
	v_pk_mul_f32 v[24:25], v[24:25], v[142:143] op_sel_hi:[1,0]
	v_pk_mul_f32 v[22:23], v[22:23], v[142:143] op_sel_hi:[1,0]
	v_pk_mul_f32 v[20:21], v[20:21], v[142:143] op_sel_hi:[1,0]
	v_pk_mul_f32 v[18:19], v[18:19], v[142:143] op_sel_hi:[1,0]
	v_pk_mul_f32 v[16:17], v[16:17], v[142:143] op_sel_hi:[1,0]
	v_pk_mul_f32 v[14:15], v[14:15], v[142:143] op_sel_hi:[1,0]
	v_pk_mul_f32 v[12:13], v[12:13], v[142:143] op_sel_hi:[1,0]
	v_pk_mul_f32 v[10:11], v[10:11], v[142:143] op_sel_hi:[1,0]
	v_pk_mul_f32 v[8:9], v[8:9], v[142:143] op_sel_hi:[1,0]
	v_pk_mul_f32 v[6:7], v[6:7], v[142:143] op_sel_hi:[1,0]
	v_pk_mul_f32 v[4:5], v[4:5], v[142:143] op_sel_hi:[1,0]
	v_pk_mul_f32 v[2:3], v[2:3], v[142:143] op_sel_hi:[1,0]
	v_pk_mul_f32 v[0:1], v[0:1], v[142:143] op_sel_hi:[1,0]
	s_branch .LBB0_964

; DI unsigned cvtpk(float lo, float hi) { f32x2_t v = {lo, hi}; bf16x2_t b = __builtin_convertvector(v, bf16x2_t); return __builtin_bit_cast(unsigned, b); }
; #define MFMA32(a, b, c) __builtin_amdgcn_mfma_f32_32x32x16_bf16((a), (b), (c), 0, 0, 0)
; #define SBAR() __builtin_amdgcn_sched_barrier(0)
; template <int VSTR, int NDVB> DI void pv64(f32x16 (&O)[NDVB], const lds8* vp, const bf16x8 (&P)[4]) {
;   bf16x8 f[2][NDVB];
; #pragma unroll
;   for (int d = 0; d < NDVB; ++d) { const s16x4 lo = trrd(vp + d * 64), hi = trrd(vp + 8 * VSTR + d * 64); f[0][d] = __builtin_shufflevector(lo, hi, 0, 1, 2, 3, 4, 5, 6, 7); }
; #pragma unroll
;   for (int kk = 0; kk < 4; ++kk) {
;     if (kk < 3) {
; #pragma unroll
;       for (int d = 0; d < NDVB; ++d) { const s16x4 lo = trrd(vp + (16 * (kk + 1)) * VSTR + d * 64), hi = trrd(vp + (16 * (kk + 1) + 8) * VSTR + d * 64);
;         f[(kk + 1) & 1][d] = __builtin_shufflevector(lo, hi, 0, 1, 2, 3, 4, 5, 6, 7); }
;     }
;     SBAR();
;     __builtin_amdgcn_s_setprio(1);
; #pragma unroll
;     for (int d = 0; d < NDVB; ++d) O[d] = MFMA32(f[kk & 1][d], P[kk], O[d]);
;     __builtin_amdgcn_s_setprio(0);
;     SBAR();
;   }
; }
; template <int NDVB, bool HAS_NEXT> DI void softmax_def(f32x16& sa0, f32x16& sa1, f32x16& sb0, f32x16& sb1, f32x16 (&O)[NDVB], float& muse, float& l, bool first, bf16x8 (&P)[4], bool check = true) {
;     ...
;   float sum = 0.f;
; #pragma unroll
;   for (int i = 0; i < 16; ++i) { sa0[i] = __builtin_amdgcn_exp2f(sa0[i]); sum += sa0[i]; }
; #pragma unroll
;   for (int i = 0; i < 16; ++i) { sa1[i] = __builtin_amdgcn_exp2f(sa1[i]); sum += sa1[i]; }
;   l += sum;
;   u32x4 w;
;   w.x = cvtpk(sa0[0], sa0[1]); w.y = cvtpk(sa0[2], sa0[3]); w.z = cvtpk(sa0[4], sa0[5]); w.w = cvtpk(sa0[6], sa0[7]); P[0] = __builtin_bit_cast(bf16x8, w);
;   w.x = cvtpk(sa0[8], sa0[9]); w.y = cvtpk(sa0[10], sa0[11]); w.z = cvtpk(sa0[12], sa0[13]); w.w = cvtpk(sa0[14], sa0[15]); P[1] = __builtin_bit_cast(bf16x8, w);
;   w.x = cvtpk(sa1[0], sa1[1]); w.y = cvtpk(sa1[2], sa1[3]); w.z = cvtpk(sa1[4], sa1[5]); w.w = cvtpk(sa1[6], sa1[7]); P[2] = __builtin_bit_cast(bf16x8, w);
;   w.x = cvtpk(sa1[8], sa1[9]); w.y = cvtpk(sa1[10], sa1[11]); w.z = cvtpk(sa1[12], sa1[13]); w.w = cvtpk(sa1[14], sa1[15]); P[3] = __builtin_bit_cast(bf16x8, w);
.LBB0_963:
	v_mov_b32_e32 v140, v139
.LBB0_964:
	v_add_u32_e32 v141, s87, v216
	ds_read_b64_tr_b16 v[154:155], v141 offset:9216
	ds_read_b64_tr_b16 v[156:157], v141 offset:10368
	ds_read_b64_tr_b16 v[178:179], v141 offset:10432
	ds_read_b64_tr_b16 v[176:177], v141 offset:9280
	ds_read_b64_tr_b16 v[180:181], v141 offset:11520
	ds_read_b64_tr_b16 v[182:183], v141 offset:12672
	ds_read_b64_tr_b16 v[222:223], v141 offset:12736
	ds_read_b64_tr_b16 v[220:221], v141 offset:11584
	v_exp_f32_e32 v112, v112
	v_exp_f32_e32 v113, v113
	v_exp_f32_e32 v114, v114
	v_exp_f32_e32 v115, v115
	v_exp_f32_e32 v116, v116
	v_exp_f32_e32 v117, v117
	v_exp_f32_e32 v118, v118
	v_exp_f32_e32 v119, v119
	v_exp_f32_e32 v120, v120
	v_exp_f32_e32 v121, v121
	v_exp_f32_e32 v122, v122
	v_exp_f32_e32 v123, v123
	v_exp_f32_e32 v124, v124
	v_exp_f32_e32 v125, v125
	v_exp_f32_e32 v126, v126
	v_exp_f32_e32 v127, v127
	v_exp_f32_e32 v96, v96
	v_exp_f32_e32 v97, v97
	v_exp_f32_e32 v98, v98
	v_exp_f32_e32 v99, v99
	v_exp_f32_e32 v100, v100
	v_exp_f32_e32 v101, v101
	v_exp_f32_e32 v102, v102
	v_exp_f32_e32 v103, v103
	v_exp_f32_e32 v104, v104
	v_exp_f32_e32 v105, v105
	v_exp_f32_e32 v106, v106
	v_exp_f32_e32 v107, v107
	v_exp_f32_e32 v108, v108
	v_exp_f32_e32 v109, v109
	v_exp_f32_e32 v110, v110
	v_exp_f32_e32 v111, v111
	v_cvt_pk_bf16_f32 v142, v112, v113
	v_cvt_pk_bf16_f32 v143, v114, v115
	v_cvt_pk_bf16_f32 v144, v116, v117
	v_cvt_pk_bf16_f32 v145, v118, v119
	v_cvt_pk_bf16_f32 v146, v120, v121
	v_cvt_pk_bf16_f32 v147, v122, v123
	v_cvt_pk_bf16_f32 v148, v124, v125
	v_cvt_pk_bf16_f32 v149, v126, v127
	v_cvt_pk_bf16_f32 v150, v96, v97
	v_cvt_pk_bf16_f32 v151, v98, v99
	v_cvt_pk_bf16_f32 v152, v100, v101
	v_cvt_pk_bf16_f32 v153, v102, v103
	v_cvt_pk_bf16_f32 v224, v104, v105
	v_cvt_pk_bf16_f32 v225, v106, v107
	v_cvt_pk_bf16_f32 v226, v108, v109
	v_cvt_pk_bf16_f32 v227, v110, v111
	s_setprio 1
	s_waitcnt lgkmcnt(6)
	v_mfma_f32_32x32x16_bf16 v[0:15], v[154:157], v[142:145], v[0:15]
	s_waitcnt lgkmcnt(4)
	v_mfma_f32_32x32x16_bf16 v[16:31], v[176:179], v[142:145], v[16:31]
	s_setprio 0
	ds_read_b64_tr_b16 v[142:143], v141 offset:13824
	ds_read_b64_tr_b16 v[144:145], v141 offset:14976
	ds_read_b64_tr_b16 v[156:157], v141 offset:15040
	ds_read_b64_tr_b16 v[154:155], v141 offset:13888
	s_setprio 1
	s_waitcnt lgkmcnt(6)
	v_mfma_f32_32x32x16_bf16 v[0:15], v[180:183], v[146:149], v[0:15]
	s_waitcnt lgkmcnt(4)
	v_mfma_f32_32x32x16_bf16 v[16:31], v[220:223], v[146:149], v[16:31]
	s_setprio 0
	ds_read_b64_tr_b16 v[146:147], v141 offset:16128
	ds_read_b64_tr_b16 v[148:149], v141 offset:17280
	ds_read_b64_tr_b16 v[178:179], v141 offset:17344
	ds_read_b64_tr_b16 v[176:177], v141 offset:16192
	s_setprio 1
	s_waitcnt lgkmcnt(6)
	v_mfma_f32_32x32x16_bf16 v[0:15], v[142:145], v[150:153], v[0:15]
	s_waitcnt lgkmcnt(4)
	v_mfma_f32_32x32x16_bf16 v[16:31], v[154:157], v[150:153], v[16:31]
	s_setprio 0
	s_setprio 1
	s_waitcnt lgkmcnt(2)
	v_mfma_f32_32x32x16_bf16 v[0:15], v[146:149], v[224:227], v[0:15]
	s_waitcnt lgkmcnt(0)
	v_mfma_f32_32x32x16_bf16 v[16:31], v[176:179], v[224:227], v[16:31]
	s_setprio 0
	s_andn2_b64 vcc, exec, s[82:83]
	s_cbranch_vccnz .LBB0_936
	s_addk_i32 s86, 0xb800
	s_cmp_lg_u32 s6, 0
	s_cselect_b32 s82, s86, 0x9000
	v_add_u32_e32 v141, s82, v215
	s_waitcnt vmcnt(1)
	ds_write_b128 v141, v[128:131]
	s_waitcnt vmcnt(0)
	ds_write_b128 v141, v[132:135] offset:9216
	s_branch .LBB0_936

; template <int MODE>
; DI void nsa_branch(lds8* lds, const bf16_t* kg, const bf16_t* vg, int pitch, unsigned tiles, const bf16x8 (&q)[4], int qpos, unsigned mybits, int blk,
;                    f32x16 (&O)[2], float& muse, float& l, int tid, int lane, int grp, CmpCap& cap) {
;     ...
;   for (int t = 0; t < ntl; ++t) {
;     NS_STEP(kra, vra, 0);
;     ++t; if (t >= ntl) break;
;     NS_STEP(kra, vra, 1);
;   }
; DI void nsa_unit(const Params& p, lds8* lds, int bl, int g, int qb32) {
;     ...
;   { const float lt = l + __shfl_xor(l, 32); const float f = g1 / lt;
; #pragma unroll
;     for (int d = 0; d < 2; ++d)
; #pragma unroll
;       for (int i = 0; i < 16; ++i) OT[d][i] += O[d][i] * f; }
.LBB0_969:
	s_mov_b64 s[10:11], -1
.LBB0_970:
	v_readlane_b32 s12, v252, 0
	v_readlane_b32 s13, v252, 1
	s_load_dwordx4 s[56:59], s[12:13], 0xa8
	v_readlane_b32 s60, v255, 12
	v_readlane_b32 s62, v255, 14
	s_mov_b64 s[72:73], s[4:5]
	v_readlane_b32 s4, v252, 7
	v_readlane_b32 s61, v255, 13
	v_readlane_b32 s63, v255, 15
	v_readlane_b32 s64, v255, 16
	s_mov_b32 s74, s2
	v_readlane_b32 s75, v255, 31
	s_mov_b32 s85, 0xefa18f08
	s_andn2_b64 vcc, exec, s[10:11]
	v_readlane_b32 s5, v252, 8
	s_cbranch_vccnz .LBB0_972
	v_mov_b32_e32 v219, v139

; DI unsigned cvtpk(float lo, float hi) { f32x2_t v = {lo, hi}; bf16x2_t b = __builtin_convertvector(v, bf16x2_t); return __builtin_bit_cast(unsigned, b); }
; #define NS_GLOAD(k_, KR, VR) do { const int jj = __builtin_amdgcn_readfirstlane(jl[(k_)]); KR = *(const u32x4*)(kg + (size_t)(64 * jj + sr) * pitch + sc * 8); VR = *(const u32x4*)(vg + (size_t)(64 * jj + sr) * pitch + sc * 8); } while (0)
; #define NS_LSTORE(st_, KR, VR) do { lds8* b = lds + (st_) * NS_STAGE; *(LAS u32x4*)(b + sr * NS_STR + sc * 16) = KR; *(LAS u32x4*)(b + 64 * NS_STR + sr * NS_STR + sc * 16) = VR; } while (0)
; template <int NDVB, bool HAS_NEXT> DI void softmax_def(f32x16& sa0, f32x16& sa1, f32x16& sb0, f32x16& sb1, f32x16 (&O)[NDVB], float& muse, float& l, bool first, bf16x8 (&P)[4], bool check = true) {
;     ...
;   float sum = 0.f;
; #pragma unroll
;   for (int i = 0; i < 16; ++i) { sa0[i] = __builtin_amdgcn_exp2f(sa0[i]); sum += sa0[i]; }
; #pragma unroll
;   for (int i = 0; i < 16; ++i) { sa1[i] = __builtin_amdgcn_exp2f(sa1[i]); sum += sa1[i]; }
;   l += sum;
;   u32x4 w;
;   w.x = cvtpk(sa0[0], sa0[1]); w.y = cvtpk(sa0[2], sa0[3]); w.z = cvtpk(sa0[4], sa0[5]); w.w = cvtpk(sa0[6], sa0[7]); P[0] = __builtin_bit_cast(bf16x8, w);
;   w.x = cvtpk(sa0[8], sa0[9]); w.y = cvtpk(sa0[10], sa0[11]); w.z = cvtpk(sa0[12], sa0[13]); w.w = cvtpk(sa0[14], sa0[15]); P[1] = __builtin_bit_cast(bf16x8, w);
;   w.x = cvtpk(sa1[0], sa1[1]); w.y = cvtpk(sa1[2], sa1[3]); w.z = cvtpk(sa1[4], sa1[5]); w.w = cvtpk(sa1[6], sa1[7]); P[2] = __builtin_bit_cast(bf16x8, w);
;   w.x = cvtpk(sa1[8], sa1[9]); w.y = cvtpk(sa1[10], sa1[11]); w.z = cvtpk(sa1[12], sa1[13]); w.w = cvtpk(sa1[14], sa1[15]); P[3] = __builtin_bit_cast(bf16x8, w);
; template <int MODE>
; DI void nsa_branch(lds8* lds, const bf16_t* kg, const bf16_t* vg, int pitch, unsigned tiles, const bf16x8 (&q)[4], int qpos, unsigned mybits, int blk,
;                    f32x16 (&O)[2], float& muse, float& l, int tid, int lane, int grp, CmpCap& cap) {
;     ...
;   NS_GLOAD(0, kra, vra); NS_LSTORE(0, kra, vra);
;   if (ntl > 1) { NS_GLOAD(1, kra, vra); NS_LSTORE(1, kra, vra); }
;   __syncthreads();
;   f32x16 s0, s1, du0, du1; bf16x8 P[4];
;   int st_cur = 0;
;     ...
;   for (int t = 0; t < ntl; ++t) {
;     NS_STEP(kra, vra, 0);
;     ++t; if (t >= ntl) break;
;     NS_STEP(kra, vra, 1);
;   }
.LBB0_994:
	v_exp_f32_e32 v141, v124
	v_add_u32_e32 v124, s49, v216
	v_exp_f32_e32 v129, v112
	v_exp_f32_e32 v130, v113
	v_exp_f32_e32 v131, v114
	v_exp_f32_e32 v132, v115
	v_exp_f32_e32 v133, v116
	v_exp_f32_e32 v134, v117
	v_exp_f32_e32 v135, v118
	v_exp_f32_e32 v136, v119
	v_exp_f32_e32 v137, v120
	v_exp_f32_e32 v138, v121
	v_exp_f32_e32 v139, v122
	v_exp_f32_e32 v140, v123
	v_exp_f32_e32 v157, v108
	v_exp_f32_e32 v158, v109
	v_exp_f32_e32 v159, v110
	v_exp_f32_e32 v222, v111
	ds_read_b64_tr_b16 v[108:109], v124 offset:9216
	ds_read_b64_tr_b16 v[110:111], v124 offset:10368
	ds_read_b64_tr_b16 v[114:115], v124 offset:10432
	ds_read_b64_tr_b16 v[112:113], v124 offset:9280
	ds_read_b64_tr_b16 v[116:117], v124 offset:11520
	ds_read_b64_tr_b16 v[118:119], v124 offset:12672
	ds_read_b64_tr_b16 v[122:123], v124 offset:12736
	ds_read_b64_tr_b16 v[120:121], v124 offset:11584
	v_exp_f32_e32 v142, v125
	v_exp_f32_e32 v143, v126
	v_exp_f32_e32 v144, v127
	v_exp_f32_e32 v145, v96
	v_exp_f32_e32 v146, v97
	v_exp_f32_e32 v147, v98
	v_exp_f32_e32 v148, v99
	v_exp_f32_e32 v149, v100
	v_exp_f32_e32 v150, v101
	v_exp_f32_e32 v151, v102
	v_exp_f32_e32 v152, v103
	v_exp_f32_e32 v153, v104
	v_exp_f32_e32 v154, v105
	v_exp_f32_e32 v155, v106
	v_exp_f32_e32 v156, v107
	v_cvt_pk_bf16_f32 v96, v129, v130
	v_cvt_pk_bf16_f32 v97, v131, v132
	v_cvt_pk_bf16_f32 v98, v133, v134
	v_cvt_pk_bf16_f32 v99, v135, v136
	v_cvt_pk_bf16_f32 v100, v137, v138
	v_cvt_pk_bf16_f32 v101, v139, v140
	v_cvt_pk_bf16_f32 v102, v141, v142
	v_cvt_pk_bf16_f32 v103, v143, v144
	v_cvt_pk_bf16_f32 v104, v145, v146
	v_cvt_pk_bf16_f32 v105, v147, v148
	v_cvt_pk_bf16_f32 v106, v149, v150
	v_cvt_pk_bf16_f32 v107, v151, v152
	v_cvt_pk_bf16_f32 v224, v153, v154
	v_cvt_pk_bf16_f32 v225, v155, v156
	v_cvt_pk_bf16_f32 v226, v157, v158
	v_cvt_pk_bf16_f32 v227, v159, v222
	s_setprio 1
	s_waitcnt lgkmcnt(6)
	v_mfma_f32_32x32x16_bf16 v[32:47], v[108:111], v[96:99], v[32:47]
	s_waitcnt lgkmcnt(4)
	v_mfma_f32_32x32x16_bf16 v[48:63], v[112:115], v[96:99], v[48:63]
	s_setprio 0
	ds_read_b64_tr_b16 v[96:97], v124 offset:13824
	ds_read_b64_tr_b16 v[98:99], v124 offset:14976
	ds_read_b64_tr_b16 v[110:111], v124 offset:15040
	ds_read_b64_tr_b16 v[108:109], v124 offset:13888
	s_setprio 1
	s_waitcnt lgkmcnt(6)
	v_mfma_f32_32x32x16_bf16 v[32:47], v[116:119], v[100:103], v[32:47]
	s_waitcnt lgkmcnt(4)
	v_mfma_f32_32x32x16_bf16 v[48:63], v[120:123], v[100:103], v[48:63]
	s_setprio 0
	ds_read_b64_tr_b16 v[112:113], v124 offset:16128
	ds_read_b64_tr_b16 v[114:115], v124 offset:17280
	ds_read_b64_tr_b16 v[230:231], v124 offset:17344
	ds_read_b64_tr_b16 v[228:229], v124 offset:16192
	s_setprio 1
	s_waitcnt lgkmcnt(6)
	v_mfma_f32_32x32x16_bf16 v[32:47], v[96:99], v[104:107], v[32:47]
	s_waitcnt lgkmcnt(4)
	v_mfma_f32_32x32x16_bf16 v[48:63], v[108:111], v[104:107], v[48:63]
	s_setprio 0
	s_setprio 1
	s_waitcnt lgkmcnt(2)
	v_mfma_f32_32x32x16_bf16 v[32:47], v[112:115], v[224:227], v[32:47]
	s_waitcnt lgkmcnt(0)
	v_mfma_f32_32x32x16_bf16 v[48:63], v[228:231], v[224:227], v[48:63]
	s_setprio 0
	s_andn2_b64 vcc, exec, s[42:43]
	s_cbranch_vccnz .LBB0_996
	s_addk_i32 s48, 0xb800
	s_cmp_lg_u32 s6, 0
	s_cselect_b32 s8, s48, 0x9000
	v_add_u32_e32 v96, s8, v215
	s_waitcnt vmcnt(1)
	ds_write_b128 v96, v[176:179]
	s_waitcnt vmcnt(0)
	ds_write_b128 v96, v[180:183] offset:9216
.LBB0_996:
	v_add_f32_e32 v96, 0, v129
	v_add_f32_e32 v96, v130, v96
	v_add_f32_e32 v96, v131, v96
	v_add_f32_e32 v96, v132, v96
	v_add_f32_e32 v96, v133, v96
	v_add_f32_e32 v96, v134, v96
	v_add_f32_e32 v96, v135, v96
	v_add_f32_e32 v96, v136, v96
	v_add_f32_e32 v96, v137, v96
	v_add_f32_e32 v96, v138, v96
	v_add_f32_e32 v96, v139, v96
	v_add_f32_e32 v96, v140, v96
	v_add_f32_e32 v96, v141, v96
	v_add_f32_e32 v96, v142, v96
	v_add_f32_e32 v96, v143, v96
	v_add_f32_e32 v96, v144, v96
	v_add_f32_e32 v96, v145, v96
	v_add_f32_e32 v96, v146, v96
	v_add_f32_e32 v96, v147, v96
	v_add_f32_e32 v96, v148, v96
	v_add_f32_e32 v96, v149, v96
	v_add_f32_e32 v96, v150, v96
	v_add_f32_e32 v96, v151, v96
	v_add_f32_e32 v96, v152, v96
	v_add_f32_e32 v96, v153, v96
	v_add_f32_e32 v96, v154, v96
	v_add_f32_e32 v96, v155, v96
	v_add_f32_e32 v96, v156, v96
	v_add_f32_e32 v96, v157, v96
	v_add_f32_e32 v96, v158, v96
	v_add_f32_e32 v96, v159, v96
	v_add_f32_e32 v96, v222, v96
	s_add_i32 s10, s46, -2
	v_add_f32_e32 v222, v128, v96
	s_mov_b64 s[8:9], -1
	s_cmp_ge_u32 s10, s3
	s_mov_b64 s[10:11], -1
	s_waitcnt lgkmcnt(0)
	s_barrier
	s_cbranch_scc1 .LBB0_980
	s_cmp_lt_u32 s46, s3
	s_cselect_b64 s[42:43], -1, 0
	s_cmp_ge_u32 s46, s3
	s_cbranch_scc1 .LBB0_999
	v_mov_b32_e32 v96, s0
	ds_read_b32 v96, v96 offset:12
	s_waitcnt lgkmcnt(0)
	v_readfirstlane_b32 s8, v96
	s_nop 1
	v_lshl_add_u32 v96, s8, 6, v212
	v_ashrrev_i32_e32 v97, 31, v96
	v_lshlrev_b64 v[96:97], 9, v[96:97]
	v_lshl_add_u64 v[98:99], v[194:195], 0, v[96:97]
	v_lshl_add_u64 v[96:97], v[196:197], 0, v[96:97]
	global_load_dwordx4 v[176:179], v[98:99], off offset:256
	global_load_dwordx4 v[180:183], v[96:97], off offset:256
; #define LAS __attribute__((address_space(3)))
; #define MFMA32(a, b, c) __builtin_amdgcn_mfma_f32_32x32x16_bf16((a), (b), (c), 0, 0, 0)
; #define SBAR() __builtin_amdgcn_sched_barrier(0)
; template <int KSTR> DI void qk64b(f32x16& s0, f32x16& s1, const lds8* kp, const bf16x8 (&q)[4], float bias) {
;   bf16x8 a[8];
; #pragma unroll
;   for (int ks = 0; ks < 4; ++ks) { a[2 * ks] = *(const LAS bf16x8*)(kp + ks * 32); a[2 * ks + 1] = *(const LAS bf16x8*)(kp + 32 * KSTR + ks * 32); }
; #pragma unroll
;   for (int i = 0; i < 16; ++i) { s0[i] = bias; s1[i] = bias; }
;   SBAR();
;   __builtin_amdgcn_s_setprio(1);
; #pragma unroll
;   for (int ks = 0; ks < 4; ++ks) { s0 = MFMA32(a[2 * ks], q[ks], s0); s1 = MFMA32(a[2 * ks + 1], q[ks], s1); }
;   __builtin_amdgcn_s_setprio(0);
;   SBAR();
; }
; template <int MODE, int SLOT> DI void ns_valu(volatile LAS int* jl, int t, int ntl, int qpos, int h, int blk, f32x16& s0, f32x16& s1, f32x16& du0, f32x16& du1, f32x16 (&O)[2], float& muse, float& l, bf16x8 (&P)[4], CmpCap& cap) {
;     ...
;         if (j == blk || j + 8 == blk) {
;           const int lim = qpos - 64 * j - 4 * h, lo = lim - 512;
; #pragma unroll
;           for (int i = 0; i < 16; ++i) { const int ci = (i & 3) + 8 * (i >> 2); if (ci > lim || ci <= lo) s0[i] = NEG; if (ci + 32 > lim || ci + 32 <= lo) s1[i] = NEG; }
;         }
.LBB0_999:
	s_add_i32 s8, s6, 1
	s_cmp_lg_u32 s6, 2
	s_cselect_b32 s6, s8, 0
	s_mul_i32 s48, s6, 0x4800
	s_add_i32 s49, s48, 0
	v_add_u32_e32 v124, s49, v213
	ds_read_b128 v[96:99], v124
	ds_read_b128 v[100:103], v124 offset:32
	ds_read_b128 v[104:107], v124 offset:4608
	ds_read_b128 v[108:111], v124 offset:4640
	ds_read_b128 v[112:115], v124 offset:64
	ds_read_b128 v[116:119], v124 offset:96
	ds_read_b128 v[120:123], v124 offset:4672
	ds_read_b128 v[124:127], v124 offset:4704
	v_xor_b32_e32 v128, 0x80000000, v221
	v_mov_b32_e32 v129, v128
	v_mov_b32_e32 v130, v128
	v_mov_b32_e32 v131, v128
	v_mov_b32_e32 v132, v128
	v_mov_b32_e32 v133, v128
	v_mov_b32_e32 v134, v128
	v_mov_b32_e32 v135, v128
	v_mov_b32_e32 v136, v128
	v_mov_b32_e32 v137, v128
	v_mov_b32_e32 v138, v128
	v_mov_b32_e32 v139, v128
	v_mov_b32_e32 v140, v128
	v_mov_b32_e32 v141, v128
	v_mov_b32_e32 v142, v128
	v_mov_b32_e32 v143, v128
	s_setprio 1
	s_waitcnt lgkmcnt(7)
	v_mfma_f32_32x32x16_bf16 v[144:159], v[96:99], v[160:163], v[128:143]
	s_waitcnt lgkmcnt(5)
	v_mfma_f32_32x32x16_bf16 v[128:143], v[104:107], v[160:163], v[128:143]
	v_mfma_f32_32x32x16_bf16 v[144:159], v[100:103], v[168:171], v[144:159]
	s_waitcnt lgkmcnt(4)
	v_mfma_f32_32x32x16_bf16 v[128:143], v[108:111], v[168:171], v[128:143]
	s_waitcnt lgkmcnt(3)
	v_mfma_f32_32x32x16_bf16 v[144:159], v[112:115], v[164:167], v[144:159]
	s_waitcnt lgkmcnt(1)
	v_mfma_f32_32x32x16_bf16 v[128:143], v[120:123], v[164:167], v[128:143]
	v_mfma_f32_32x32x16_bf16 v[144:159], v[116:119], v[172:175], v[144:159]
	s_waitcnt lgkmcnt(0)
	v_mfma_f32_32x32x16_bf16 v[128:143], v[124:127], v[172:175], v[128:143]
	s_setprio 0
	v_mov_b32_e32 v96, s0
	ds_read_b32 v96, v96 offset:4
	s_waitcnt lgkmcnt(0)
	v_readfirstlane_b32 s8, v96
	s_cmp_eq_u32 s8, s77
	s_cselect_b64 s[10:11], -1, 0
	s_add_i32 s9, s8, 8
	s_cmp_eq_u32 s9, s77
	s_cselect_b64 s[12:13], -1, 0
	s_or_b64 s[10:11], s[10:11], s[12:13]
	s_andn2_b64 vcc, exec, s[10:11]
	s_cbranch_vccnz .LBB0_1003
	v_lshl_or_b32 v96, s8, 6, v214
	v_sub_u32_e32 v96, v211, v96
	v_subrev_u32_e32 v97, 32, v96
	v_cmp_gt_u32_e64 s[8:9], s33, v97
	v_add_u32_e32 v97, -1, v96
	v_cmp_gt_u32_e32 vcc, s33, v96
	v_cndmask_b32_e64 v128, v207, v128, s[8:9]
	v_cmp_gt_u32_e64 s[8:9], s33, v97
	v_subrev_u32_e32 v97, 33, v96
	v_cmp_gt_u32_e64 s[10:11], s33, v97
	v_add_u32_e32 v97, -2, v96
	s_nop 0
	v_cndmask_b32_e64 v129, v207, v129, s[10:11]
	v_cmp_gt_u32_e64 s[10:11], s33, v97
	v_subrev_u32_e32 v97, 34, v96
	v_cmp_gt_u32_e64 s[12:13], s33, v97
	v_add_u32_e32 v97, -3, v96
	s_nop 0
	v_cndmask_b32_e64 v130, v207, v130, s[12:13]
	v_cmp_gt_u32_e64 s[12:13], s33, v97
	v_subrev_u32_e32 v97, 35, v96
	v_cmp_gt_u32_e64 s[14:15], s33, v97
	v_add_u32_e32 v97, -8, v96
	s_nop 0
	v_cndmask_b32_e64 v131, v207, v131, s[14:15]
	v_cmp_gt_u32_e64 s[14:15], s33, v97
	v_subrev_u32_e32 v97, 40, v96
	v_cmp_gt_u32_e64 s[16:17], s33, v97
	v_add_u32_e32 v97, -9, v96
	s_nop 0
	v_cndmask_b32_e64 v132, v207, v132, s[16:17]
	v_cmp_gt_u32_e64 s[16:17], s33, v97
	v_subrev_u32_e32 v97, 41, v96
	v_cmp_gt_u32_e64 s[18:19], s33, v97
	v_add_u32_e32 v97, -10, v96
	s_nop 0
	v_cndmask_b32_e64 v133, v207, v133, s[18:19]
	v_cmp_gt_u32_e64 s[18:19], s33, v97
	v_subrev_u32_e32 v97, 42, v96
	v_cmp_gt_u32_e64 s[20:21], s33, v97
	v_add_u32_e32 v97, -11, v96
	s_nop 0
	v_cndmask_b32_e64 v134, v207, v134, s[20:21]
	v_cmp_gt_u32_e64 s[20:21], s33, v97
	v_subrev_u32_e32 v97, 43, v96
	v_cmp_gt_u32_e64 s[22:23], s33, v97
	v_add_u32_e32 v97, -16, v96
	s_nop 0
	v_cndmask_b32_e64 v135, v207, v135, s[22:23]
	v_cmp_gt_u32_e64 s[22:23], s33, v97
	v_subrev_u32_e32 v97, 48, v96
	v_cmp_gt_u32_e64 s[24:25], s33, v97
	v_subrev_u32_e32 v97, 17, v96
	s_nop 0
	v_cndmask_b32_e64 v136, v207, v136, s[24:25]
	v_cmp_gt_u32_e64 s[24:25], s33, v97
	v_subrev_u32_e32 v97, 49, v96
	v_cmp_gt_u32_e64 s[26:27], s33, v97
	v_subrev_u32_e32 v97, 18, v96
	s_nop 0
	v_cndmask_b32_e64 v137, v207, v137, s[26:27]
	v_cmp_gt_u32_e64 s[26:27], s33, v97
	v_subrev_u32_e32 v97, 50, v96
	v_cmp_gt_u32_e64 s[28:29], s33, v97
	v_subrev_u32_e32 v97, 19, v96
	s_nop 0
	v_cndmask_b32_e64 v138, v207, v138, s[28:29]
	v_cmp_gt_u32_e64 s[28:29], s33, v97
	v_subrev_u32_e32 v97, 51, v96
	v_cmp_gt_u32_e64 s[30:31], s33, v97
	v_subrev_u32_e32 v97, 24, v96
	s_nop 0
	v_cndmask_b32_e64 v139, v207, v139, s[30:31]
	v_cmp_gt_u32_e64 s[30:31], s33, v97
	v_subrev_u32_e32 v97, 56, v96
	v_cmp_gt_u32_e64 s[34:35], s33, v97
	v_subrev_u32_e32 v97, 25, v96
	s_nop 0
	v_cndmask_b32_e64 v140, v207, v140, s[34:35]
	v_cmp_gt_u32_e64 s[34:35], s33, v97
	v_subrev_u32_e32 v97, 57, v96
	v_cmp_gt_u32_e64 s[36:37], s33, v97
	v_subrev_u32_e32 v97, 26, v96
	s_nop 0
	v_cndmask_b32_e64 v141, v207, v141, s[36:37]
	v_cmp_gt_u32_e64 s[36:37], s33, v97
	v_subrev_u32_e32 v97, 58, v96
	v_cmp_gt_u32_e64 s[38:39], s33, v97
	v_subrev_u32_e32 v97, 27, v96
	v_subrev_u32_e32 v96, 59, v96
	v_cndmask_b32_e64 v142, v207, v142, s[38:39]
	v_cmp_gt_u32_e64 s[38:39], s33, v97
	v_cmp_lt_u32_e64 s[40:41], s95, v96
	s_and_saveexec_b64 s[44:45], s[40:41]
	s_mov_b32 s1, 0xf149f2ca
	v_mov_b32_e32 v143, s1
	s_or_b64 exec, exec, s[44:45]
	v_cndmask_b32_e32 v144, v207, v144, vcc
	v_cndmask_b32_e64 v145, v207, v145, s[8:9]
	v_cndmask_b32_e64 v146, v207, v146, s[10:11]
	v_cndmask_b32_e64 v147, v207, v147, s[12:13]
	v_cndmask_b32_e64 v148, v207, v148, s[14:15]
	v_cndmask_b32_e64 v149, v207, v149, s[16:17]
	v_cndmask_b32_e64 v150, v207, v150, s[18:19]
	v_cndmask_b32_e64 v151, v207, v151, s[20:21]
	v_cndmask_b32_e64 v152, v207, v152, s[22:23]
	v_cndmask_b32_e64 v153, v207, v153, s[24:25]
	v_cndmask_b32_e64 v154, v207, v154, s[26:27]
	v_cndmask_b32_e64 v155, v207, v155, s[28:29]
	v_cndmask_b32_e64 v156, v207, v156, s[30:31]
	v_cndmask_b32_e64 v157, v207, v157, s[34:35]
	v_cndmask_b32_e64 v158, v207, v158, s[36:37]
	v_cndmask_b32_e64 v159, v207, v159, s[38:39]
; DI float rowmax32(const f32x16& s0, const f32x16& s1) {
;   float a = fmaxf(fmaxf(s0[0], s0[1]), s1[0]), b = fmaxf(fmaxf(s0[2], s0[3]), s1[1]); a = fmaxf(fmaxf(a, s1[2]), s1[3]);
; #pragma unroll
;   for (int r = 4; r < 16; r += 4) { a = fmaxf(fmaxf(a, s0[r]), s0[r + 1]); b = fmaxf(fmaxf(b, s0[r + 2]), s0[r + 3]); a = fmaxf(fmaxf(a, s1[r]), s1[r + 1]); b = fmaxf(fmaxf(b, s1[r + 2]), s1[r + 3]); }
;   const float m = fmaxf(a, b);
;   return fmaxf(m, __shfl_xor(m, 32));
; }
; template <int NDVB, bool HAS_NEXT> DI void softmax_def(f32x16& sa0, f32x16& sa1, f32x16& sb0, f32x16& sb1, f32x16 (&O)[NDVB], float& muse, float& l, bool first, bf16x8 (&P)[4], bool check = true) {
;   float mx = 0.f;
;   if (check) mx = rowmax32(sa0, sa1);
;   if (check && (first || __any(mx > 8.f))) {
;     float dl = first ? mx : fmaxf(mx, 0.f);
;     if (mx < -1e29f) dl = 0.f;
;     const float alpha = __builtin_amdgcn_exp2f(-dl);
;     muse += dl; l *= alpha;
; #pragma unroll
;     for (int i = 0; i < 16; ++i) { sa0[i] -= dl; sa1[i] -= dl; }
;     if (HAS_NEXT) {
; #pragma unroll
;       for (int i = 0; i < 16; ++i) { sb0[i] -= dl; sb1[i] -= dl; }
;     }
; #pragma unroll
;     for (int d = 0; d < NDVB; ++d)
; #pragma unroll
;       for (int i = 0; i < 16; ++i) O[d][i] *= alpha;
;   }
.LBB0_1003:
	v_max_f32_e32 v96, v145, v145
	v_max_f32_e32 v97, v144, v144
	v_max_f32_e32 v96, v97, v96
	v_max3_f32 v97, v146, v147, v129
	v_max3_f32 v96, v96, v128, v130
	v_max3_f32 v96, v96, v131, v148
	v_max3_f32 v97, v97, v150, v151
	v_max3_f32 v96, v96, v149, v132
	v_max3_f32 v97, v97, v134, v135
	v_max3_f32 v96, v96, v133, v152
	v_max3_f32 v97, v97, v154, v155
	v_max3_f32 v96, v96, v153, v136
	v_max3_f32 v97, v97, v138, v139
	v_max3_f32 v96, v96, v137, v156
	v_max3_f32 v97, v97, v158, v159
	v_max3_f32 v96, v96, v157, v140
	v_max3_f32 v97, v97, v142, v143
	v_max3_f32 v96, v96, v141, v97
	ds_bpermute_b32 v97, v193, v96
	s_waitcnt lgkmcnt(0)
	v_max_f32_e32 v97, v97, v97
	v_max_f32_e32 v96, v96, v97
	v_cmp_lt_f32_e32 vcc, s7, v96
	s_cbranch_vccz .LBB0_1006
	v_max_f32_e32 v97, v96, v96
	v_max_f32_e32 v97, 0, v97
	v_cmp_ngt_f32_e32 vcc, s85, v96
	s_nop 1
	v_cndmask_b32_e32 v96, 0, v97, vcc
	v_exp_f32_e64 v188, -v96
	v_add_f32_e32 v221, v221, v96
	v_pk_add_f32 v[144:145], v[144:145], v[96:97] op_sel_hi:[1,0] neg_lo:[0,1] neg_hi:[0,1]
	v_pk_add_f32 v[128:129], v[128:129], v[96:97] op_sel_hi:[1,0] neg_lo:[0,1] neg_hi:[0,1]
	v_mul_f32_e32 v223, v222, v188
	v_pk_add_f32 v[146:147], v[146:147], v[96:97] op_sel_hi:[1,0] neg_lo:[0,1] neg_hi:[0,1]
	v_pk_add_f32 v[130:131], v[130:131], v[96:97] op_sel_hi:[1,0] neg_lo:[0,1] neg_hi:[0,1]
	v_pk_add_f32 v[148:149], v[148:149], v[96:97] op_sel_hi:[1,0] neg_lo:[0,1] neg_hi:[0,1]
	v_pk_add_f32 v[132:133], v[132:133], v[96:97] op_sel_hi:[1,0] neg_lo:[0,1] neg_hi:[0,1]
	v_pk_add_f32 v[150:151], v[150:151], v[96:97] op_sel_hi:[1,0] neg_lo:[0,1] neg_hi:[0,1]
	v_pk_add_f32 v[134:135], v[134:135], v[96:97] op_sel_hi:[1,0] neg_lo:[0,1] neg_hi:[0,1]
	v_pk_add_f32 v[152:153], v[152:153], v[96:97] op_sel_hi:[1,0] neg_lo:[0,1] neg_hi:[0,1]
	v_pk_add_f32 v[136:137], v[136:137], v[96:97] op_sel_hi:[1,0] neg_lo:[0,1] neg_hi:[0,1]
	v_pk_add_f32 v[154:155], v[154:155], v[96:97] op_sel_hi:[1,0] neg_lo:[0,1] neg_hi:[0,1]
	v_pk_add_f32 v[138:139], v[138:139], v[96:97] op_sel_hi:[1,0] neg_lo:[0,1] neg_hi:[0,1]
	v_pk_add_f32 v[156:157], v[156:157], v[96:97] op_sel_hi:[1,0] neg_lo:[0,1] neg_hi:[0,1]
	v_pk_add_f32 v[140:141], v[140:141], v[96:97] op_sel_hi:[1,0] neg_lo:[0,1] neg_hi:[0,1]
	v_pk_add_f32 v[158:159], v[158:159], v[96:97] op_sel_hi:[1,0] neg_lo:[0,1] neg_hi:[0,1]
	v_pk_add_f32 v[142:143], v[142:143], v[96:97] op_sel_hi:[1,0] neg_lo:[0,1] neg_hi:[0,1]
	v_pk_mul_f32 v[62:63], v[62:63], v[188:189] op_sel_hi:[1,0]
	v_pk_mul_f32 v[60:61], v[60:61], v[188:189] op_sel_hi:[1,0]
	v_pk_mul_f32 v[58:59], v[58:59], v[188:189] op_sel_hi:[1,0]
	v_pk_mul_f32 v[56:57], v[56:57], v[188:189] op_sel_hi:[1,0]
	v_pk_mul_f32 v[54:55], v[54:55], v[188:189] op_sel_hi:[1,0]
	v_pk_mul_f32 v[52:53], v[52:53], v[188:189] op_sel_hi:[1,0]
	v_pk_mul_f32 v[50:51], v[50:51], v[188:189] op_sel_hi:[1,0]
	v_pk_mul_f32 v[48:49], v[48:49], v[188:189] op_sel_hi:[1,0]
	v_pk_mul_f32 v[46:47], v[46:47], v[188:189] op_sel_hi:[1,0]
	v_pk_mul_f32 v[44:45], v[44:45], v[188:189] op_sel_hi:[1,0]
	v_pk_mul_f32 v[42:43], v[42:43], v[188:189] op_sel_hi:[1,0]
	v_pk_mul_f32 v[40:41], v[40:41], v[188:189] op_sel_hi:[1,0]
	v_pk_mul_f32 v[38:39], v[38:39], v[188:189] op_sel_hi:[1,0]
	v_pk_mul_f32 v[36:37], v[36:37], v[188:189] op_sel_hi:[1,0]
	v_pk_mul_f32 v[34:35], v[34:35], v[188:189] op_sel_hi:[1,0]
	v_pk_mul_f32 v[32:33], v[32:33], v[188:189] op_sel_hi:[1,0]
	s_branch .LBB0_1007

; DI unsigned cvtpk(float lo, float hi) { f32x2_t v = {lo, hi}; bf16x2_t b = __builtin_convertvector(v, bf16x2_t); return __builtin_bit_cast(unsigned, b); }
; #define MFMA32(a, b, c) __builtin_amdgcn_mfma_f32_32x32x16_bf16((a), (b), (c), 0, 0, 0)
; #define SBAR() __builtin_amdgcn_sched_barrier(0)
; template <int VSTR, int NDVB> DI void pv64(f32x16 (&O)[NDVB], const lds8* vp, const bf16x8 (&P)[4]) {
;   bf16x8 f[2][NDVB];
; #pragma unroll
;   for (int d = 0; d < NDVB; ++d) { const s16x4 lo = trrd(vp + d * 64), hi = trrd(vp + 8 * VSTR + d * 64); f[0][d] = __builtin_shufflevector(lo, hi, 0, 1, 2, 3, 4, 5, 6, 7); }
; #pragma unroll
;   for (int kk = 0; kk < 4; ++kk) {
;     if (kk < 3) {
; #pragma unroll
;       for (int d = 0; d < NDVB; ++d) { const s16x4 lo = trrd(vp + (16 * (kk + 1)) * VSTR + d * 64), hi = trrd(vp + (16 * (kk + 1) + 8) * VSTR + d * 64);
;         f[(kk + 1) & 1][d] = __builtin_shufflevector(lo, hi, 0, 1, 2, 3, 4, 5, 6, 7); }
;     }
;     SBAR();
;     __builtin_amdgcn_s_setprio(1);
; #pragma unroll
;     for (int d = 0; d < NDVB; ++d) O[d] = MFMA32(f[kk & 1][d], P[kk], O[d]);
;     __builtin_amdgcn_s_setprio(0);
;     SBAR();
;   }
; }
; template <int NDVB, bool HAS_NEXT> DI void softmax_def(f32x16& sa0, f32x16& sa1, f32x16& sb0, f32x16& sb1, f32x16 (&O)[NDVB], float& muse, float& l, bool first, bf16x8 (&P)[4], bool check = true) {
;     ...
;   float sum = 0.f;
; #pragma unroll
;   for (int i = 0; i < 16; ++i) { sa0[i] = __builtin_amdgcn_exp2f(sa0[i]); sum += sa0[i]; }
; #pragma unroll
;   for (int i = 0; i < 16; ++i) { sa1[i] = __builtin_amdgcn_exp2f(sa1[i]); sum += sa1[i]; }
;   l += sum;
;   u32x4 w;
;   w.x = cvtpk(sa0[0], sa0[1]); w.y = cvtpk(sa0[2], sa0[3]); w.z = cvtpk(sa0[4], sa0[5]); w.w = cvtpk(sa0[6], sa0[7]); P[0] = __builtin_bit_cast(bf16x8, w);
;   w.x = cvtpk(sa0[8], sa0[9]); w.y = cvtpk(sa0[10], sa0[11]); w.z = cvtpk(sa0[12], sa0[13]); w.w = cvtpk(sa0[14], sa0[15]); P[1] = __builtin_bit_cast(bf16x8, w);
;   w.x = cvtpk(sa1[0], sa1[1]); w.y = cvtpk(sa1[2], sa1[3]); w.z = cvtpk(sa1[4], sa1[5]); w.w = cvtpk(sa1[6], sa1[7]); P[2] = __builtin_bit_cast(bf16x8, w);
;   w.x = cvtpk(sa1[8], sa1[9]); w.y = cvtpk(sa1[10], sa1[11]); w.z = cvtpk(sa1[12], sa1[13]); w.w = cvtpk(sa1[14], sa1[15]); P[3] = __builtin_bit_cast(bf16x8, w);
.LBB0_1006:
	v_mov_b32_e32 v223, v222
.LBB0_1007:
	v_add_u32_e32 v206, s49, v216
	ds_read_b64_tr_b16 v[236:237], v206 offset:9216
	ds_read_b64_tr_b16 v[238:239], v206 offset:10368
	ds_read_b64_tr_b16 v[242:243], v206 offset:10432
	ds_read_b64_tr_b16 v[240:241], v206 offset:9280
	ds_read_b64_tr_b16 v[244:245], v206 offset:11520
	ds_read_b64_tr_b16 v[246:247], v206 offset:12672
	ds_read_b64_tr_b16 v[250:251], v206 offset:12736
	ds_read_b64_tr_b16 v[248:249], v206 offset:11584
	v_exp_f32_e32 v144, v144
	v_exp_f32_e32 v145, v145
	v_exp_f32_e32 v146, v146
	v_exp_f32_e32 v147, v147
	v_exp_f32_e32 v148, v148
	v_exp_f32_e32 v149, v149
	v_exp_f32_e32 v150, v150
	v_exp_f32_e32 v151, v151
	v_exp_f32_e32 v152, v152
	v_exp_f32_e32 v153, v153
	v_exp_f32_e32 v154, v154
	v_exp_f32_e32 v155, v155
	v_exp_f32_e32 v156, v156
	v_exp_f32_e32 v157, v157
	v_exp_f32_e32 v158, v158
	v_exp_f32_e32 v159, v159
	v_exp_f32_e32 v128, v128
	v_exp_f32_e32 v129, v129
	v_exp_f32_e32 v130, v130
	v_exp_f32_e32 v131, v131
	v_exp_f32_e32 v132, v132
	v_exp_f32_e32 v133, v133
	v_exp_f32_e32 v134, v134
	v_exp_f32_e32 v135, v135
	v_exp_f32_e32 v136, v136
	v_exp_f32_e32 v137, v137
	v_exp_f32_e32 v138, v138
	v_exp_f32_e32 v139, v139
	v_exp_f32_e32 v140, v140
	v_exp_f32_e32 v141, v141
	v_exp_f32_e32 v142, v142
	v_exp_f32_e32 v143, v143
	v_cvt_pk_bf16_f32 v224, v144, v145
	v_cvt_pk_bf16_f32 v225, v146, v147
	v_cvt_pk_bf16_f32 v226, v148, v149
	v_cvt_pk_bf16_f32 v227, v150, v151
	v_cvt_pk_bf16_f32 v228, v152, v153
	v_cvt_pk_bf16_f32 v229, v154, v155
	v_cvt_pk_bf16_f32 v230, v156, v157
	v_cvt_pk_bf16_f32 v231, v158, v159
	v_cvt_pk_bf16_f32 v232, v128, v129
	v_cvt_pk_bf16_f32 v233, v130, v131
	v_cvt_pk_bf16_f32 v234, v132, v133
	v_cvt_pk_bf16_f32 v235, v134, v135
	v_cvt_pk_bf16_f32 v188, v136, v137
	v_cvt_pk_bf16_f32 v189, v138, v139
	v_cvt_pk_bf16_f32 v190, v140, v141
	v_cvt_pk_bf16_f32 v191, v142, v143
	s_setprio 1
	s_waitcnt lgkmcnt(6)
	v_mfma_f32_32x32x16_bf16 v[32:47], v[236:239], v[224:227], v[32:47]
	s_waitcnt lgkmcnt(4)
	v_mfma_f32_32x32x16_bf16 v[48:63], v[240:243], v[224:227], v[48:63]
	s_setprio 0
	ds_read_b64_tr_b16 v[224:225], v206 offset:13824
	ds_read_b64_tr_b16 v[226:227], v206 offset:14976
	ds_read_b64_tr_b16 v[238:239], v206 offset:15040
	ds_read_b64_tr_b16 v[236:237], v206 offset:13888
	s_setprio 1
	s_waitcnt lgkmcnt(6)
	v_mfma_f32_32x32x16_bf16 v[32:47], v[244:247], v[228:231], v[32:47]
	s_waitcnt lgkmcnt(4)
	v_mfma_f32_32x32x16_bf16 v[48:63], v[248:251], v[228:231], v[48:63]
	s_setprio 0
	ds_read_b64_tr_b16 v[228:229], v206 offset:16128
	ds_read_b64_tr_b16 v[230:231], v206 offset:17280
	ds_read_b64_tr_b16 v[242:243], v206 offset:17344
	ds_read_b64_tr_b16 v[240:241], v206 offset:16192
	s_setprio 1
	s_waitcnt lgkmcnt(6)
	v_mfma_f32_32x32x16_bf16 v[32:47], v[224:227], v[232:235], v[32:47]
	s_waitcnt lgkmcnt(4)
	v_mfma_f32_32x32x16_bf16 v[48:63], v[236:239], v[232:235], v[48:63]
	s_setprio 0
	s_setprio 1
	s_waitcnt lgkmcnt(2)
	v_mfma_f32_32x32x16_bf16 v[32:47], v[228:231], v[188:191], v[32:47]
	s_waitcnt lgkmcnt(0)
	v_mfma_f32_32x32x16_bf16 v[48:63], v[240:243], v[188:191], v[48:63]
	s_setprio 0
	s_andn2_b64 vcc, exec, s[42:43]
	s_cbranch_vccnz .LBB0_979
	s_addk_i32 s48, 0xb800
	s_cmp_lg_u32 s6, 0
	s_cselect_b32 s8, s48, 0x9000
	v_add_u32_e32 v188, s8, v215
	s_waitcnt vmcnt(1)
	ds_write_b128 v188, v[176:179]
	s_waitcnt vmcnt(0)
	ds_write_b128 v188, v[180:183] offset:9216
	s_branch .LBB0_979

; template <int MODE>
; DI void nsa_branch(lds8* lds, const bf16_t* kg, const bf16_t* vg, int pitch, unsigned tiles, const bf16x8 (&q)[4], int qpos, unsigned mybits, int blk,
;                    f32x16 (&O)[2], float& muse, float& l, int tid, int lane, int grp, CmpCap& cap) {
;     ...
;   for (int t = 0; t < ntl; ++t) {
;     NS_STEP(kra, vra, 0);
;     ++t; if (t >= ntl) break;
;     NS_STEP(kra, vra, 1);
;   }
.LBB0_1012:
.LBB0_1013:
	v_mov_b32_e32 v128, v222
